# LRU scan loops: mid-issue waitcnt (first consumer scheduled between loads) moved after the last load so all 16/12 row loads are in flight together
# baseline (speedup 1.0000x reference)
; __device__ __forceinline__ unsigned pk2(float lo, float hi) { f32x2_t v = {lo, hi}; bf16x2_t b = __builtin_convertvector(v, bf16x2_t); return __builtin_bit_cast(unsigned, b); }
; #define UNPK8(V_) {bf_lo((V_).x), bf_hi((V_).x), bf_lo((V_).y), bf_hi((V_).y), bf_lo((V_).z), bf_hi((V_).z), bf_lo((V_).w), bf_hi((V_).w)}
; __global__ void __launch_bounds__(NTHR, 2) fwd_kernel(Args args) {
;     ...
; #pragma unroll 1
;                     for (int r0 = 0; r0 < 16; r0 += 4) {
;                         u32x4 la[4], gx[4], xc[4], gb[4];
; #pragma unroll
;                         for (int i = 0; i < 4; ++i) { la[i] = *(const u32x4*)(LA + rbase + (size_t)(r0 + i) * D); gx[i] = *(const u32x4*)(GX + rbase + (size_t)(r0 + i) * D); xc[i] = *(const u32x4*)(XC + rbase + (size_t)(r0 + i) * D); gb[i] = *(const u32x4*)(GB + rbase + (size_t)(r0 + i) * D); }
; #pragma unroll
;                         for (int i = 0; i < 4; ++i) { const float l[8] = UNPK8(la[i]), g[8] = UNPK8(gx[i]), x[8] = UNPK8(xc[i]), gg[8] = UNPK8(gb[i]); float y[8];
; #pragma unroll
;                             for (int e = 0; e < 8; ++e) { H[e] = __expf(l[e]) * H[e] + g[e] * x[e]; y[e] = gg[e] * H[e]; }
;                             u32x4 w; w.x = pk2(y[0], y[1]); w.y = pk2(y[2], y[3]); w.z = pk2(y[4], y[5]); w.w = pk2(y[6], y[7]);
;                             *(u32x4*)(YB + rbase + (size_t)(r0 + i) * D) = w; }
;                     }
.LBB0_275:
	s_nop 0
	v_add_co_u32_e32 v8, vcc, 0xfbfff000, v56
	s_mov_b32 s3, 0xfa000000
	s_nop 0
	v_addc_co_u32_e32 v9, vcc, -1, v57, vcc
	global_load_dwordx4 v[58:61], v[8:9], off offset:-2048
	v_add_co_u32_e32 v10, vcc, 0xfffff000, v56
	s_add_i32 s2, s2, 4
	s_nop 0
	v_addc_co_u32_e32 v11, vcc, -1, v57, vcc
	global_load_dwordx4 v[44:47], v[10:11], off offset:-2048
	v_add_co_u32_e32 v10, vcc, 0xfdfff000, v56
	s_cmp_gt_u32 s2, 11
	s_nop 0
	v_addc_co_u32_e32 v11, vcc, -1, v57, vcc
	v_add_co_u32_e32 v12, vcc, 0xf9fff000, v56
	global_load_dwordx4 v[48:51], v[10:11], off offset:-2048
	s_nop 0
	v_addc_co_u32_e32 v13, vcc, -1, v57, vcc
	global_load_dwordx4 v[52:55], v[12:13], off offset:-2048
	global_load_dwordx4 v[70:73], v[8:9], off
	global_load_dwordx4 v[40:43], v[56:57], off offset:-4096
	global_load_dwordx4 v[36:39], v[10:11], off
	global_load_dwordx4 v[32:35], v[12:13], off
	v_add_co_u32_e32 v20, vcc, s15, v56
	s_nop 1
	v_addc_co_u32_e32 v21, vcc, -1, v57, vcc
	global_load_dwordx4 v[74:77], v[20:21], off offset:-2048
	global_load_dwordx4 v[8:11], v[56:57], off offset:-2048
	v_add_co_u32_e32 v22, vcc, s24, v56
	s_nop 1
	v_addc_co_u32_e32 v23, vcc, -1, v57, vcc
	v_add_co_u32_e32 v62, vcc, s3, v56
	global_load_dwordx4 v[12:15], v[22:23], off offset:-2048
	s_nop 0
	v_addc_co_u32_e32 v63, vcc, -1, v57, vcc
	global_load_dwordx4 v[16:19], v[62:63], off offset:-2048
	global_load_dwordx4 v[78:81], v[20:21], off
	global_load_dwordx4 v[28:31], v[56:57], off
	global_load_dwordx4 v[24:27], v[22:23], off
	s_nop 0
	global_load_dwordx4 v[20:23], v[62:63], off
	s_waitcnt vmcnt(15)
	v_lshlrev_b32_e32 v86, 16, v61
	v_and_b32_e32 v87, 0xffff0000, v61
	v_lshlrev_b32_e32 v62, 16, v58
	v_and_b32_e32 v58, 0xffff0000, v58
	v_lshlrev_b32_e32 v63, 16, v59
	v_mul_f32_e32 v58, 0x3fb8aa3b, v58
	v_and_b32_e32 v59, 0xffff0000, v59
	v_exp_f32_e32 v61, v58
	v_mul_f32_e32 v58, 0x3fb8aa3b, v63
	v_lshlrev_b32_e32 v84, 16, v60
	v_exp_f32_e32 v82, v58
	v_mul_f32_e32 v58, 0x3fb8aa3b, v59
	v_and_b32_e32 v85, 0xffff0000, v60
	v_exp_f32_e32 v83, v58
	v_mul_f32_e32 v58, 0x3fb8aa3b, v84
	v_exp_f32_e32 v84, v58
	v_mul_f32_e32 v58, 0x3fb8aa3b, v85
	v_exp_f32_e32 v85, v58
	v_mul_f32_e32 v58, 0x3fb8aa3b, v86
	v_exp_f32_e32 v86, v58
	v_mul_f32_e32 v58, 0x3fb8aa3b, v87
	v_exp_f32_e32 v87, v58
	s_waitcnt vmcnt(11)
	v_lshlrev_b32_e32 v58, 16, v70
	v_and_b32_e32 v59, 0xffff0000, v70
	v_mul_f32_e32 v58, 0x3fb8aa3b, v58
	v_mul_f32_e32 v60, 0x3fb8aa3b, v62
	v_lshlrev_b32_e32 v62, 16, v71
	v_exp_f32_e32 v70, v58
	v_mul_f32_e32 v58, 0x3fb8aa3b, v59
	v_and_b32_e32 v63, 0xffff0000, v71
	v_exp_f32_e32 v71, v58
	v_mul_f32_e32 v58, 0x3fb8aa3b, v62
	v_lshlrev_b32_e32 v88, 16, v72
	v_and_b32_e32 v89, 0xffff0000, v72
	v_exp_f32_e32 v72, v58
	v_mul_f32_e32 v58, 0x3fb8aa3b, v63
	v_lshlrev_b32_e32 v90, 16, v73
	v_and_b32_e32 v91, 0xffff0000, v73
	v_exp_f32_e32 v73, v58
	v_mul_f32_e32 v58, 0x3fb8aa3b, v88
	v_exp_f32_e32 v88, v58
	v_mul_f32_e32 v58, 0x3fb8aa3b, v89
	v_exp_f32_e32 v89, v58
	v_mul_f32_e32 v58, 0x3fb8aa3b, v90
	v_exp_f32_e32 v62, v58
	v_mul_f32_e32 v58, 0x3fb8aa3b, v91
	v_exp_f32_e32 v63, v58
	v_exp_f32_e32 v60, v60
	s_mov_b32 s3, 0xf43ff000
	s_waitcnt vmcnt(7)
	v_lshlrev_b32_e32 v58, 16, v74
	v_and_b32_e32 v59, 0xffff0000, v74
	v_mul_f32_e32 v58, 0x3fb8aa3b, v58
	v_lshlrev_b32_e32 v90, 16, v75
	v_exp_f32_e32 v74, v58
	v_mul_f32_e32 v58, 0x3fb8aa3b, v59
	v_and_b32_e32 v91, 0xffff0000, v75
	v_exp_f32_e32 v75, v58
	v_mul_f32_e32 v58, 0x3fb8aa3b, v90
	v_lshlrev_b32_e32 v92, 16, v76
	v_and_b32_e32 v93, 0xffff0000, v76
	v_exp_f32_e32 v76, v58
	v_mul_f32_e32 v58, 0x3fb8aa3b, v91
	v_lshlrev_b32_e32 v94, 16, v77
	v_and_b32_e32 v95, 0xffff0000, v77
	v_exp_f32_e32 v77, v58
	v_mul_f32_e32 v58, 0x3fb8aa3b, v92
	v_exp_f32_e32 v90, v58
	v_mul_f32_e32 v58, 0x3fb8aa3b, v93
	s_waitcnt vmcnt(3)
	v_lshlrev_b32_e32 v92, 16, v78
	v_and_b32_e32 v93, 0xffff0000, v78
	v_exp_f32_e32 v91, v58
	v_mul_f32_e32 v58, 0x3fb8aa3b, v94
	v_mul_f32_e32 v59, 0x3fb8aa3b, v95
	v_lshlrev_b32_e32 v94, 16, v79
	v_and_b32_e32 v95, 0xffff0000, v79
	v_lshlrev_b32_e32 v96, 16, v80
	v_and_b32_e32 v97, 0xffff0000, v80
	v_lshlrev_b32_e32 v98, 16, v81
	v_and_b32_e32 v99, 0xffff0000, v81
	v_mul_f32_e32 v78, 0x3fb8aa3b, v92
	v_mul_f32_e32 v79, 0x3fb8aa3b, v93
	v_and_b32_e32 v81, 0xffff0000, v44
	v_lshlrev_b32_e32 v80, 16, v44
	v_and_b32_e32 v93, 0xffff0000, v48
	v_lshlrev_b32_e32 v92, 16, v48
	v_pk_mul_f32 v[80:81], v[80:81], v[92:93]
	v_exp_f32_e32 v78, v78
	s_waitcnt lgkmcnt(1)
	v_pk_fma_f32 v[0:1], v[0:1], v[60:61], v[80:81]
	v_lshlrev_b32_e32 v60, 16, v52
	v_and_b32_e32 v61, 0xffff0000, v52
	v_pk_mul_f32 v[60:61], v[0:1], v[60:61]
	v_and_b32_e32 v81, 0xffff0000, v36
	v_cvt_pk_bf16_f32 v44, v60, v61
	v_and_b32_e32 v61, 0xffff0000, v40
	v_lshlrev_b32_e32 v60, 16, v40
	v_lshlrev_b32_e32 v80, 16, v36
	v_pk_mul_f32 v[60:61], v[60:61], v[80:81]
	v_exp_f32_e32 v79, v79
	v_pk_fma_f32 v[0:1], v[0:1], v[70:71], v[60:61]
	v_lshlrev_b32_e32 v60, 16, v32
	v_and_b32_e32 v61, 0xffff0000, v32
	v_pk_mul_f32 v[60:61], v[0:1], v[60:61]
	v_and_b32_e32 v71, 0xffff0000, v12
	v_cvt_pk_bf16_f32 v32, v60, v61
	v_and_b32_e32 v61, 0xffff0000, v8
	v_lshlrev_b32_e32 v60, 16, v8
	v_lshlrev_b32_e32 v70, 16, v12
	v_pk_mul_f32 v[60:61], v[60:61], v[70:71]
	s_waitcnt vmcnt(1)
; __device__ __forceinline__ unsigned pk2(float lo, float hi) { f32x2_t v = {lo, hi}; bf16x2_t b = __builtin_convertvector(v, bf16x2_t); return __builtin_bit_cast(unsigned, b); }
; #define UNPK8(V_) {bf_lo((V_).x), bf_hi((V_).x), bf_lo((V_).y), bf_hi((V_).y), bf_lo((V_).z), bf_hi((V_).z), bf_lo((V_).w), bf_hi((V_).w)}
; __global__ void __launch_bounds__(NTHR, 2) fwd_kernel(Args args) {
;     ...
; #pragma unroll 1
;                     for (int r0 = 0; r0 < 16; r0 += 4) {
;                         u32x4 la[4], gx[4], xc[4], gb[4];
; #pragma unroll
;                         for (int i = 0; i < 4; ++i) { la[i] = *(const u32x4*)(LA + rbase + (size_t)(r0 + i) * D); gx[i] = *(const u32x4*)(GX + rbase + (size_t)(r0 + i) * D); xc[i] = *(const u32x4*)(XC + rbase + (size_t)(r0 + i) * D); gb[i] = *(const u32x4*)(GB + rbase + (size_t)(r0 + i) * D); }
; #pragma unroll
;                         for (int i = 0; i < 4; ++i) { const float l[8] = UNPK8(la[i]), g[8] = UNPK8(gx[i]), x[8] = UNPK8(xc[i]), gg[8] = UNPK8(gb[i]); float y[8];
; #pragma unroll
;                             for (int e = 0; e < 8; ++e) { H[e] = __expf(l[e]) * H[e] + g[e] * x[e]; y[e] = gg[e] * H[e]; }
;                             u32x4 w; w.x = pk2(y[0], y[1]); w.y = pk2(y[2], y[3]); w.z = pk2(y[4], y[5]); w.w = pk2(y[6], y[7]);
;                             *(u32x4*)(YB + rbase + (size_t)(r0 + i) * D) = w; }
;                     }
;                     __syncthreads();
	v_and_b32_e32 v71, 0xffff0000, v24
	v_pk_fma_f32 v[0:1], v[0:1], v[74:75], v[60:61]
	v_lshlrev_b32_e32 v60, 16, v16
	v_and_b32_e32 v61, 0xffff0000, v16
	v_pk_mul_f32 v[60:61], v[0:1], v[60:61]
	v_lshlrev_b32_e32 v70, 16, v24
	v_cvt_pk_bf16_f32 v8, v60, v61
	v_and_b32_e32 v61, 0xffff0000, v28
	v_lshlrev_b32_e32 v60, 16, v28
	v_pk_mul_f32 v[60:61], v[60:61], v[70:71]
	v_and_b32_e32 v75, 0xffff0000, v45
	v_pk_fma_f32 v[0:1], v[0:1], v[78:79], v[60:61]
	v_lshlrev_b32_e32 v74, 16, v45
	v_and_b32_e32 v79, 0xffff0000, v49
	v_lshlrev_b32_e32 v78, 16, v49
	v_pk_mul_f32 v[48:49], v[74:75], v[78:79]
	v_lshlrev_b32_e32 v40, 16, v37
	v_pk_fma_f32 v[2:3], v[2:3], v[82:83], v[48:49]
	v_lshlrev_b32_e32 v48, 16, v53
	v_and_b32_e32 v49, 0xffff0000, v53
	v_pk_mul_f32 v[48:49], v[2:3], v[48:49]
	v_mul_f32_e32 v12, 0x3fb8aa3b, v94
	v_cvt_pk_bf16_f32 v45, v48, v49
	v_and_b32_e32 v49, 0xffff0000, v41
	v_lshlrev_b32_e32 v48, 16, v41
	v_and_b32_e32 v41, 0xffff0000, v37
	v_pk_mul_f32 v[36:37], v[48:49], v[40:41]
	v_exp_f32_e32 v70, v12
	v_pk_fma_f32 v[2:3], v[2:3], v[72:73], v[36:37]
	v_lshlrev_b32_e32 v36, 16, v33
	v_and_b32_e32 v37, 0xffff0000, v33
	v_pk_mul_f32 v[36:37], v[2:3], v[36:37]
	v_mul_f32_e32 v12, 0x3fb8aa3b, v95
	v_cvt_pk_bf16_f32 v33, v36, v37
	v_and_b32_e32 v37, 0xffff0000, v9
	v_lshlrev_b32_e32 v36, 16, v9
	v_and_b32_e32 v41, 0xffff0000, v13
	v_lshlrev_b32_e32 v40, 16, v13
	v_exp_f32_e32 v71, v12
	v_pk_mul_f32 v[12:13], v[36:37], v[40:41]
	v_lshlrev_b32_e32 v16, 16, v25
	v_pk_fma_f32 v[2:3], v[2:3], v[76:77], v[12:13]
	v_lshlrev_b32_e32 v12, 16, v17
	v_and_b32_e32 v13, 0xffff0000, v17
	v_pk_mul_f32 v[12:13], v[2:3], v[12:13]
	v_and_b32_e32 v17, 0xffff0000, v25
	v_cvt_pk_bf16_f32 v9, v12, v13
	v_and_b32_e32 v13, 0xffff0000, v29
	v_lshlrev_b32_e32 v12, 16, v29
	v_pk_mul_f32 v[12:13], v[12:13], v[16:17]
	s_waitcnt vmcnt(0)
	v_lshlrev_b32_e32 v60, 16, v20
	v_and_b32_e32 v61, 0xffff0000, v20
	v_pk_fma_f32 v[2:3], v[2:3], v[70:71], v[12:13]
	v_lshlrev_b32_e32 v12, 16, v21
	v_and_b32_e32 v13, 0xffff0000, v21
	v_and_b32_e32 v21, 0xffff0000, v46
	v_lshlrev_b32_e32 v20, 16, v46
	v_and_b32_e32 v25, 0xffff0000, v50
	v_lshlrev_b32_e32 v24, 16, v50
	v_pk_mul_f32 v[20:21], v[20:21], v[24:25]
	v_and_b32_e32 v25, 0xffff0000, v38
	s_waitcnt lgkmcnt(0)
	v_pk_fma_f32 v[4:5], v[4:5], v[84:85], v[20:21]
	v_lshlrev_b32_e32 v20, 16, v54
	v_and_b32_e32 v21, 0xffff0000, v54
	v_pk_mul_f32 v[20:21], v[4:5], v[20:21]
	v_lshlrev_b32_e32 v24, 16, v38
	v_cvt_pk_bf16_f32 v46, v20, v21
	v_and_b32_e32 v21, 0xffff0000, v42
	v_lshlrev_b32_e32 v20, 16, v42
	v_pk_mul_f32 v[20:21], v[20:21], v[24:25]
	v_and_b32_e32 v25, 0xffff0000, v14
	v_pk_fma_f32 v[4:5], v[4:5], v[88:89], v[20:21]
	v_lshlrev_b32_e32 v20, 16, v34
	v_and_b32_e32 v21, 0xffff0000, v34
	v_pk_mul_f32 v[20:21], v[4:5], v[20:21]
	v_lshlrev_b32_e32 v24, 16, v14
	v_cvt_pk_bf16_f32 v34, v20, v21
	v_and_b32_e32 v21, 0xffff0000, v10
	v_lshlrev_b32_e32 v20, 16, v10
	v_pk_mul_f32 v[20:21], v[20:21], v[24:25]
	v_and_b32_e32 v25, 0xffff0000, v26
	v_pk_fma_f32 v[4:5], v[4:5], v[90:91], v[20:21]
	v_lshlrev_b32_e32 v20, 16, v18
	v_and_b32_e32 v21, 0xffff0000, v18
	v_pk_mul_f32 v[20:21], v[4:5], v[20:21]
	v_lshlrev_b32_e32 v24, 16, v26
	v_cvt_pk_bf16_f32 v10, v20, v21
	v_and_b32_e32 v21, 0xffff0000, v30
	v_lshlrev_b32_e32 v20, 16, v30
	v_pk_mul_f32 v[20:21], v[20:21], v[24:25]
	v_and_b32_e32 v25, 0xffff0000, v47
	v_lshlrev_b32_e32 v24, 16, v47
	v_and_b32_e32 v29, 0xffff0000, v51
	v_lshlrev_b32_e32 v28, 16, v51
	v_pk_mul_f32 v[24:25], v[24:25], v[28:29]
	v_and_b32_e32 v29, 0xffff0000, v39
	v_pk_fma_f32 v[6:7], v[6:7], v[86:87], v[24:25]
	v_lshlrev_b32_e32 v24, 16, v55
	v_and_b32_e32 v25, 0xffff0000, v55
	v_pk_mul_f32 v[24:25], v[6:7], v[24:25]
	v_lshlrev_b32_e32 v28, 16, v39
	v_cvt_pk_bf16_f32 v47, v24, v25
	v_add_co_u32_e32 v24, vcc, s3, v56
	v_mul_f32_e32 v16, 0x3fb8aa3b, v96
	s_nop 0
	v_addc_co_u32_e32 v25, vcc, -1, v57, vcc
	global_store_dwordx4 v[24:25], v[44:47], off offset:-2048
	v_and_b32_e32 v25, 0xffff0000, v43
	v_lshlrev_b32_e32 v24, 16, v43
	v_mul_f32_e32 v17, 0x3fb8aa3b, v97
	v_pk_mul_f32 v[24:25], v[24:25], v[28:29]
	v_exp_f32_e32 v16, v16
	v_exp_f32_e32 v17, v17
	v_pk_fma_f32 v[6:7], v[6:7], v[62:63], v[24:25]
	v_lshlrev_b32_e32 v24, 16, v35
	v_and_b32_e32 v25, 0xffff0000, v35
	v_pk_mul_f32 v[24:25], v[6:7], v[24:25]
	s_mov_b32 s3, 0xf4400000
	v_exp_f32_e32 v58, v58
	v_exp_f32_e32 v59, v59
	v_cvt_pk_bf16_f32 v35, v24, v25
	v_add_co_u32_e32 v24, vcc, s3, v56
	v_mul_f32_e32 v14, 0x3fb8aa3b, v98
	s_nop 0
	v_addc_co_u32_e32 v25, vcc, -1, v57, vcc
	v_pk_fma_f32 v[4:5], v[4:5], v[16:17], v[20:21]
	v_exp_f32_e32 v20, v14
	v_mul_f32_e32 v14, 0x3fb8aa3b, v99
	global_store_dwordx4 v[24:25], v[32:35], off offset:-4096
	v_and_b32_e32 v29, 0xffff0000, v11
	v_lshlrev_b32_e32 v28, 16, v11
	v_and_b32_e32 v33, 0xffff0000, v15
	v_lshlrev_b32_e32 v32, 16, v15
	v_exp_f32_e32 v21, v14
	v_pk_mul_f32 v[14:15], v[28:29], v[32:33]
	v_lshlrev_b32_e32 v16, 16, v22
	v_pk_fma_f32 v[6:7], v[6:7], v[58:59], v[14:15]
	v_lshlrev_b32_e32 v14, 16, v19
	v_and_b32_e32 v15, 0xffff0000, v19
	v_pk_mul_f32 v[14:15], v[6:7], v[14:15]
	v_and_b32_e32 v17, 0xffff0000, v22
	v_cvt_pk_bf16_f32 v11, v14, v15
	global_store_dwordx4 v[24:25], v[8:11], off offset:-2048
	v_pk_mul_f32 v[60:61], v[0:1], v[60:61]
	v_pk_mul_f32 v[12:13], v[2:3], v[12:13]
	v_and_b32_e32 v9, 0xffff0000, v31
	v_lshlrev_b32_e32 v8, 16, v31
	v_and_b32_e32 v11, 0xffff0000, v27
	v_lshlrev_b32_e32 v10, 16, v27
	v_pk_mul_f32 v[8:9], v[8:9], v[10:11]
	v_pk_mul_f32 v[16:17], v[4:5], v[16:17]
	v_pk_fma_f32 v[6:7], v[6:7], v[20:21], v[8:9]
	v_lshlrev_b32_e32 v8, 16, v23
	v_and_b32_e32 v9, 0xffff0000, v23
	v_pk_mul_f32 v[14:15], v[6:7], v[8:9]
	v_cvt_pk_bf16_f32 v8, v60, v61
	v_cvt_pk_bf16_f32 v9, v12, v13
	v_cvt_pk_bf16_f32 v10, v16, v17
	v_cvt_pk_bf16_f32 v11, v14, v15
	v_lshl_add_u64 v[56:57], v[56:57], 0, s[42:43]
	global_store_dwordx4 v[24:25], v[8:11], off
	s_cbranch_scc0 .LBB0_275
	s_add_i32 s13, s13, s30
	s_add_i32 s22, s22, s4
	s_cmpk_gt_i32 s13, 0xff
	v_lshl_add_u64 v[68:69], v[68:69], 0, s[38:39]
	s_barrier
	s_cbranch_scc0 .LBB0_235

; #define UNPK8(V_) {bf_lo((V_).x), bf_hi((V_).x), bf_lo((V_).y), bf_hi((V_).y), bf_lo((V_).z), bf_hi((V_).z), bf_lo((V_).w), bf_hi((V_).w)}
; __global__ void __launch_bounds__(NTHR, 2) fwd_kernel(Args args) {
;     ...
; #pragma unroll 1
;                     for (int r0 = 0; r0 < 16; r0 += 4) {
;                         u32x4 la[4], gx[4], xc[4];
; #pragma unroll
;                         for (int i = 0; i < 4; ++i) { la[i] = *(const u32x4*)(LA + rbase + (size_t)(r0 + i) * D); gx[i] = *(const u32x4*)(GX + rbase + (size_t)(r0 + i) * D); xc[i] = *(const u32x4*)(XC + rbase + (size_t)(r0 + i) * D); }
; #pragma unroll
;                         for (int i = 0; i < 4; ++i) { const float l[8] = UNPK8(la[i]), g[8] = UNPK8(gx[i]), x[8] = UNPK8(xc[i]);
; #pragma unroll
;                             for (int e = 0; e < 8; ++e) { H[e] = __expf(l[e]) * H[e] + g[e] * x[e]; Ls[e] += l[e]; } }
.LBB0_285:
	s_mov_b32 s3, 0xfbfff000
	v_add_co_u32_e64 v44, s[38:39], s3, v16
	s_movk_i32 s3, 0xf000
	s_nop 0
	v_addc_co_u32_e64 v45, s[38:39], -1, v17, s[38:39]
	global_load_dwordx4 v[44:47], v[44:45], off offset:-2048
	v_add_co_u32_e64 v48, s[38:39], s3, v16
	s_mov_b32 s3, 0xfdfff000
	s_nop 0
	v_addc_co_u32_e64 v49, s[38:39], -1, v17, s[38:39]
	global_load_dwordx4 v[48:51], v[48:49], off offset:-2048
	v_add_co_u32_e64 v52, s[38:39], s3, v16
	s_add_i32 s2, s2, 4
	s_nop 0
	v_addc_co_u32_e64 v53, s[38:39], -1, v17, s[38:39]
	global_load_dwordx4 v[52:55], v[52:53], off offset:-2048
	v_add_co_u32_e64 v80, s[38:39], s15, v16
	s_cmp_gt_u32 s2, 11
	s_nop 0
	v_addc_co_u32_e64 v81, s[38:39], -1, v17, s[38:39]
	global_load_dwordx4 v[56:59], v[80:81], off offset:-4096
	global_load_dwordx4 v[60:63], v[16:17], off offset:-4096
	v_add_co_u32_e64 v88, s[38:39], s24, v16
	s_nop 1
	v_addc_co_u32_e64 v89, s[38:39], -1, v17, s[38:39]
	global_load_dwordx4 v[64:67], v[88:89], off offset:-4096
	global_load_dwordx4 v[68:71], v[80:81], off offset:-2048
	global_load_dwordx4 v[72:75], v[16:17], off offset:-2048
	global_load_dwordx4 v[76:79], v[88:89], off offset:-2048
	s_nop 0
	global_load_dwordx4 v[80:83], v[80:81], off
	s_nop 0
	global_load_dwordx4 v[84:87], v[16:17], off
	s_nop 0
	global_load_dwordx4 v[88:91], v[88:89], off
	s_waitcnt vmcnt(11)
	v_lshlrev_b32_e32 v3, 16, v44
	v_and_b32_e32 v43, 0xffff0000, v44
	v_lshlrev_b32_e32 v92, 16, v45
	v_lshlrev_b32_e32 v94, 16, v46
	v_and_b32_e32 v95, 0xffff0000, v46
	v_mul_f32_e32 v44, 0x3fb8aa3b, v3
	v_add_f32_e32 v46, v12, v3
	v_mul_f32_e32 v3, 0x3fb8aa3b, v43
	v_and_b32_e32 v93, 0xffff0000, v45
	v_exp_f32_e32 v12, v3
	v_mul_f32_e32 v3, 0x3fb8aa3b, v92
	s_waitcnt vmcnt(10)
	v_lshlrev_b32_e32 v45, 16, v48
	v_and_b32_e32 v13, 0xffff0000, v48
	v_add_f32_e32 v48, v14, v43
	v_exp_f32_e32 v14, v3
	v_mul_f32_e32 v3, 0x3fb8aa3b, v93
	v_lshlrev_b32_e32 v11, 16, v50
	v_and_b32_e32 v5, 0xffff0000, v50
	v_add_f32_e32 v50, v8, v92
	v_exp_f32_e32 v8, v3
	v_mul_f32_e32 v3, 0x3fb8aa3b, v94
	v_lshlrev_b32_e32 v96, 16, v47
	s_waitcnt vmcnt(9)
	v_lshlrev_b32_e32 v39, 16, v52
	v_and_b32_e32 v37, 0xffff0000, v52
	v_add_f32_e32 v52, v10, v93
	v_exp_f32_e32 v10, v3
	v_mul_f32_e32 v3, 0x3fb8aa3b, v95
	v_lshlrev_b32_e32 v25, 16, v54
	v_and_b32_e32 v23, 0xffff0000, v54
	v_exp_f32_e32 v44, v44
	v_add_f32_e32 v54, v4, v94
	v_exp_f32_e32 v4, v3
	v_mul_f32_e32 v3, 0x3fb8aa3b, v96
	v_add_f32_e32 v94, v0, v96
	s_waitcnt vmcnt(8)
	v_lshlrev_b32_e32 v96, 16, v56
	v_lshlrev_b32_e32 v104, 16, v59
	v_and_b32_e32 v106, 0xffff0000, v59
	v_mul_f32_e32 v59, 0x3fb8aa3b, v96
	v_exp_f32_e32 v108, v59
	s_waitcnt vmcnt(7)
	v_lshlrev_b32_e32 v109, 16, v60
	v_and_b32_e32 v111, 0xffff0000, v60
	v_lshlrev_b32_e32 v113, 16, v61
	v_and_b32_e32 v61, 0xffff0000, v61
	v_mul_f32_e32 v60, v45, v39
	v_add_f32_e32 v92, v6, v95
	v_exp_f32_e32 v6, v3
	v_pk_fma_f32 v[38:39], v[44:45], v[38:39], v[60:61] op_sel_hi:[1,1,0]
	v_and_b32_e32 v56, 0xffff0000, v56
	v_lshlrev_b32_e32 v98, 16, v57
	v_lshlrev_b32_e32 v15, 16, v49
	v_lshlrev_b32_e32 v35, 16, v53
	v_and_b32_e32 v47, 0xffff0000, v47
	v_mul_f32_e32 v0, 0x3fb8aa3b, v47
	v_add_f32_e32 v2, v2, v47
	v_and_b32_e32 v100, 0xffff0000, v57
	v_and_b32_e32 v9, 0xffff0000, v49
	v_and_b32_e32 v27, 0xffff0000, v53
	v_lshlrev_b32_e32 v102, 16, v58
	v_lshlrev_b32_e32 v7, 16, v51
	v_and_b32_e32 v1, 0xffff0000, v51
	v_lshlrev_b32_e32 v115, 16, v62
	v_and_b32_e32 v58, 0xffff0000, v58
	v_and_b32_e32 v117, 0xffff0000, v62
	v_lshlrev_b32_e32 v21, 16, v55
	v_and_b32_e32 v19, 0xffff0000, v55
	v_lshlrev_b32_e32 v119, 16, v63
	v_exp_f32_e32 v0, v0
	v_and_b32_e32 v63, 0xffff0000, v63
	v_lshl_add_u64 v[16:17], v[16:17], 0, s[42:43]
	s_waitcnt vmcnt(6)
	v_lshlrev_b32_e32 v3, 16, v64
	v_mov_b32_e32 v39, v3
	v_pk_mul_f32 v[38:39], v[108:109], v[38:39]
	v_and_b32_e32 v43, 0xffff0000, v64
	v_add_f32_e32 v3, v38, v39
	v_mul_f32_e32 v38, 0x3fb8aa3b, v56
	v_exp_f32_e32 v110, v38
	v_mul_f32_e32 v38, v13, v37
	v_pk_fma_f32 v[12:13], v[12:13], v[36:37], v[38:39] op_sel_hi:[1,1,0]
	v_lshlrev_b32_e32 v47, 16, v65
	v_mov_b32_e32 v13, v43
	v_pk_mul_f32 v[12:13], v[110:111], v[12:13]
	v_and_b32_e32 v49, 0xffff0000, v65
	v_add_f32_e32 v36, v12, v13
	v_mul_f32_e32 v12, 0x3fb8aa3b, v98
	v_exp_f32_e32 v112, v12
	v_mul_f32_e32 v12, v15, v35
	v_pk_fma_f32 v[12:13], v[14:15], v[34:35], v[12:13] op_sel_hi:[1,1,0]
	v_lshlrev_b32_e32 v51, 16, v66
	v_mov_b32_e32 v13, v47
	v_pk_mul_f32 v[12:13], v[112:113], v[12:13]
	v_and_b32_e32 v53, 0xffff0000, v66
	v_add_f32_e32 v34, v12, v13
	v_mul_f32_e32 v12, 0x3fb8aa3b, v100
	v_exp_f32_e32 v60, v12
	v_mul_f32_e32 v12, v9, v27
	v_pk_fma_f32 v[8:9], v[8:9], v[26:27], v[12:13] op_sel_hi:[1,1,0]
	v_lshlrev_b32_e32 v55, 16, v67
	v_mov_b32_e32 v9, v49
	v_pk_mul_f32 v[8:9], v[60:61], v[8:9]
	v_and_b32_e32 v57, 0xffff0000, v67
	v_add_f32_e32 v35, v8, v9
	v_mul_f32_e32 v8, 0x3fb8aa3b, v102
	v_exp_f32_e32 v114, v8
	v_mul_f32_e32 v8, v11, v25
	v_pk_fma_f32 v[8:9], v[10:11], v[24:25], v[8:9] op_sel_hi:[1,1,0]
	s_waitcnt vmcnt(5)
	v_and_b32_e32 v10, 0xffff0000, v69
	v_mov_b32_e32 v9, v51
	v_pk_mul_f32 v[8:9], v[114:115], v[8:9]
	v_and_b32_e32 v24, 0xffff0000, v71
	v_add_f32_e32 v11, v8, v9
	v_mul_f32_e32 v8, 0x3fb8aa3b, v58
	v_exp_f32_e32 v116, v8
	v_mul_f32_e32 v8, v5, v23
	v_pk_fma_f32 v[4:5], v[4:5], v[22:23], v[8:9] op_sel_hi:[1,1,0]
	v_lshlrev_b32_e32 v22, 16, v71
	v_mov_b32_e32 v5, v53
	v_pk_mul_f32 v[4:5], v[116:117], v[4:5]
	s_waitcnt vmcnt(3)
; #define UNPK8(V_) {bf_lo((V_).x), bf_hi((V_).x), bf_lo((V_).y), bf_hi((V_).y), bf_lo((V_).z), bf_hi((V_).z), bf_lo((V_).w), bf_hi((V_).w)}
; __global__ void __launch_bounds__(NTHR, 2) fwd_kernel(Args args) {
;     ...
;                         for (int i = 0; i < 4; ++i) { const float l[8] = UNPK8(la[i]), g[8] = UNPK8(gx[i]), x[8] = UNPK8(xc[i]);
; #pragma unroll
;                             for (int e = 0; e < 8; ++e) { H[e] = __expf(l[e]) * H[e] + g[e] * x[e]; Ls[e] += l[e]; } }
;                     }
;                     float* c2 = CAR2 + ((size_t)(task * 4 + sub) * D + c8) * 2;
; #pragma unroll
;                     for (int e = 0; e < 8; e += 2) *(f32x4*)(c2 + 2 * e) = (f32x4){Ls[e], H[e], Ls[e + 1], H[e + 1]};
;                     if (sub != 0) {
; #pragma unroll
;                         for (int e = 0; e < 8; ++e) { xs[(sub * 1024 + c8 + e) * 2] = Ls[e]; xs[(sub * 1024 + c8 + e) * 2 + 1] = H[e]; }
	v_and_b32_e32 v13, 0xffff0000, v77
	v_add_f32_e32 v23, v4, v5
	v_mul_f32_e32 v4, 0x3fb8aa3b, v104
	v_exp_f32_e32 v118, v4
	v_mul_f32_e32 v4, v7, v21
	v_pk_fma_f32 v[4:5], v[6:7], v[20:21], v[4:5] op_sel_hi:[1,1,0]
	v_lshlrev_b32_e32 v6, 16, v69
	v_mov_b32_e32 v5, v55
	v_pk_mul_f32 v[4:5], v[118:119], v[4:5]
	v_and_b32_e32 v20, 0xffff0000, v70
	v_add_f32_e32 v5, v4, v5
	v_mul_f32_e32 v4, 0x3fb8aa3b, v106
	v_exp_f32_e32 v62, v4
	v_mul_f32_e32 v4, v1, v19
	v_pk_fma_f32 v[0:1], v[0:1], v[18:19], v[4:5] op_sel_hi:[1,1,0]
	v_and_b32_e32 v4, 0xffff0000, v68
	v_mov_b32_e32 v1, v57
	v_pk_mul_f32 v[0:1], v[62:63], v[0:1]
	v_lshlrev_b32_e32 v18, 16, v70
	v_add_f32_e32 v1, v0, v1
	v_lshlrev_b32_e32 v0, 16, v68
	v_mul_f32_e32 v44, 0x3fb8aa3b, v0
	v_exp_f32_e32 v44, v44
	v_and_b32_e32 v12, 0xffff0000, v73
	v_lshlrev_b32_e32 v7, 16, v76
	v_lshlrev_b32_e32 v19, 16, v72
	v_mul_f32_e32 v97, v44, v3
	v_mul_f32_e32 v3, 0x3fb8aa3b, v4
	v_exp_f32_e32 v3, v3
	v_mul_f32_e32 v47, v19, v7
	v_lshlrev_b32_e32 v37, 16, v78
	v_lshlrev_b32_e32 v38, 16, v74
	v_mul_f32_e32 v57, v3, v36
	v_mul_f32_e32 v3, 0x3fb8aa3b, v6
	v_exp_f32_e32 v3, v3
	v_and_b32_e32 v15, 0xffff0000, v78
	v_and_b32_e32 v14, 0xffff0000, v74
	v_pk_add_f32 v[46:47], v[46:47], v[96:97]
	v_mul_f32_e32 v99, v3, v34
	v_mul_f32_e32 v3, 0x3fb8aa3b, v10
	v_exp_f32_e32 v3, v3
	v_and_b32_e32 v9, 0xffff0000, v76
	v_and_b32_e32 v8, 0xffff0000, v72
	v_lshlrev_b32_e32 v21, 16, v77
	v_mul_f32_e32 v101, v3, v35
	v_mul_f32_e32 v3, 0x3fb8aa3b, v18
	v_exp_f32_e32 v3, v3
	v_pk_mul_f32 v[34:35], v[12:13], v[12:13] op_sel_hi:[0,1]
	s_waitcnt vmcnt(2)
	v_lshlrev_b32_e32 v12, 16, v80
	v_mul_f32_e32 v55, v38, v37
	v_mul_f32_e32 v103, v3, v11
	v_mul_f32_e32 v3, 0x3fb8aa3b, v20
	v_exp_f32_e32 v3, v3
	v_pk_mul_f32 v[36:37], v[14:15], v[14:15] op_sel_hi:[0,1]
	s_waitcnt vmcnt(1)
	v_lshlrev_b32_e32 v14, 16, v84
	v_pk_mul_f32 v[8:9], v[8:9], v[8:9] op_sel_hi:[0,1]
	v_mul_f32_e32 v59, v3, v23
	v_mul_f32_e32 v3, 0x3fb8aa3b, v22
	v_exp_f32_e32 v3, v3
	s_waitcnt vmcnt(0)
	v_lshlrev_b32_e32 v15, 16, v88
	v_and_b32_e32 v8, 0xffff0000, v80
	v_mov_b32_e32 v49, v9
	v_mul_f32_e32 v105, v3, v5
	v_mul_f32_e32 v3, 0x3fb8aa3b, v24
	v_exp_f32_e32 v3, v3
	v_and_b32_e32 v63, 0xffff0000, v88
	v_and_b32_e32 v62, 0xffff0000, v84
	v_lshlrev_b32_e32 v38, 16, v81
	v_mul_f32_e32 v107, v3, v1
	v_mul_f32_e32 v1, 0x3fb8aa3b, v12
	v_exp_f32_e32 v1, v1
	v_lshlrev_b32_e32 v25, 16, v73
	v_mul_f32_e32 v51, v25, v21
	v_lshlrev_b32_e32 v64, 16, v85
	v_pk_add_f32 v[76:77], v[46:47], v[0:1]
	v_pk_mul_f32 v[0:1], v[46:47], v[0:1]
	v_lshlrev_b32_e32 v65, 16, v89
	v_mov_b32_e32 v77, v1
	v_mov_b32_e32 v1, v14
	v_pk_mul_f32 v[0:1], v[0:1], v[14:15]
	v_and_b32_e32 v34, 0xffff0000, v81
	v_mul_f32_e32 v0, 0x3fb8aa3b, v8
	v_exp_f32_e32 v5, v0
	v_mov_b32_e32 v13, v1
	v_pk_add_f32 v[0:1], v[48:49], v[56:57]
	v_lshlrev_b32_e32 v39, 16, v79
	v_pk_add_f32 v[14:15], v[0:1], v[4:5]
	v_pk_mul_f32 v[0:1], v[0:1], v[4:5]
	v_lshlrev_b32_e32 v43, 16, v75
	v_mov_b32_e32 v15, v1
	v_pk_mul_f32 v[0:1], v[62:63], v[62:63] op_sel_hi:[0,1]
	v_mul_f32_e32 v0, 0x3fb8aa3b, v38
	v_exp_f32_e32 v7, v0
	v_mov_b32_e32 v9, v1
	v_pk_add_f32 v[0:1], v[50:51], v[98:99]
	v_mov_b32_e32 v53, v35
	v_pk_add_f32 v[4:5], v[0:1], v[6:7]
	v_pk_mul_f32 v[0:1], v[0:1], v[6:7]
	v_mul_f32_e32 v95, v43, v39
	v_mov_b32_e32 v5, v1
	v_mov_b32_e32 v1, v64
	v_pk_mul_f32 v[0:1], v[0:1], v[64:65]
	v_and_b32_e32 v67, 0xffff0000, v89
	v_mul_f32_e32 v0, 0x3fb8aa3b, v34
	v_exp_f32_e32 v11, v0
	v_mov_b32_e32 v39, v1
	v_pk_add_f32 v[0:1], v[52:53], v[100:101]
	v_and_b32_e32 v66, 0xffff0000, v85
	v_pk_add_f32 v[14:15], v[14:15], v[8:9]
	v_pk_add_f32 v[8:9], v[4:5], v[38:39]
	v_pk_add_f32 v[4:5], v[0:1], v[10:11]
	v_pk_mul_f32 v[0:1], v[0:1], v[10:11]
	v_lshlrev_b32_e32 v44, 16, v82
	v_mov_b32_e32 v5, v1
	v_pk_mul_f32 v[0:1], v[66:67], v[66:67] op_sel_hi:[0,1]
	v_mul_f32_e32 v0, 0x3fb8aa3b, v44
	v_exp_f32_e32 v19, v0
	v_mov_b32_e32 v35, v1
	v_pk_add_f32 v[0:1], v[54:55], v[102:103]
	v_lshlrev_b32_e32 v68, 16, v86
	v_pk_add_f32 v[10:11], v[4:5], v[34:35]
	v_pk_add_f32 v[4:5], v[0:1], v[18:19]
	v_pk_mul_f32 v[0:1], v[0:1], v[18:19]
	v_lshlrev_b32_e32 v69, 16, v90
	v_mov_b32_e32 v5, v1
	v_mov_b32_e32 v1, v68
	v_and_b32_e32 v36, 0xffff0000, v82
	v_pk_mul_f32 v[0:1], v[0:1], v[68:69]
	v_mov_b32_e32 v93, v37
	v_mul_f32_e32 v0, 0x3fb8aa3b, v36
	v_exp_f32_e32 v21, v0
	v_mov_b32_e32 v45, v1
	v_pk_add_f32 v[0:1], v[92:93], v[58:59]
	v_and_b32_e32 v71, 0xffff0000, v90
	v_and_b32_e32 v70, 0xffff0000, v86
	v_pk_add_f32 v[6:7], v[0:1], v[20:21]
	v_pk_mul_f32 v[0:1], v[0:1], v[20:21]
	v_lshlrev_b32_e32 v60, 16, v83
	v_mov_b32_e32 v7, v1
	v_pk_mul_f32 v[0:1], v[70:71], v[70:71] op_sel_hi:[0,1]
	v_mul_f32_e32 v0, 0x3fb8aa3b, v60
	v_and_b32_e32 v27, 0xffff0000, v79
	v_and_b32_e32 v26, 0xffff0000, v75
	v_exp_f32_e32 v23, v0
	v_pk_mul_f32 v[26:27], v[26:27], v[26:27] op_sel_hi:[0,1]
	v_and_b32_e32 v26, 0xffff0000, v83
	v_mov_b32_e32 v37, v1
	v_pk_add_f32 v[0:1], v[94:95], v[104:105]
	v_mul_f32_e32 v3, 0x3fb8aa3b, v26
	v_lshlrev_b32_e32 v72, 16, v87
	v_pk_add_f32 v[18:19], v[0:1], v[22:23]
	v_pk_mul_f32 v[0:1], v[0:1], v[22:23]
	v_exp_f32_e32 v25, v3
	v_lshlrev_b32_e32 v73, 16, v91
	v_mov_b32_e32 v19, v1
	v_mov_b32_e32 v1, v72
	v_pk_mul_f32 v[0:1], v[0:1], v[72:73]
	v_mov_b32_e32 v3, v27
	v_mov_b32_e32 v61, v1
	v_pk_add_f32 v[2:3], v[2:3], v[106:107]
	v_and_b32_e32 v75, 0xffff0000, v91
	v_and_b32_e32 v74, 0xffff0000, v87
	v_pk_add_f32 v[0:1], v[18:19], v[60:61]
	v_pk_add_f32 v[18:19], v[2:3], v[24:25]
	v_pk_mul_f32 v[2:3], v[2:3], v[24:25]
	v_pk_add_f32 v[12:13], v[76:77], v[12:13]
	v_mov_b32_e32 v19, v3
	v_pk_mul_f32 v[2:3], v[74:75], v[74:75] op_sel_hi:[0,1]
	v_mov_b32_e32 v27, v3
	v_pk_add_f32 v[4:5], v[4:5], v[44:45]
	v_pk_add_f32 v[6:7], v[6:7], v[36:37]
	v_pk_add_f32 v[2:3], v[18:19], v[26:27]
	v_mov_b32_e32 v20, v1
	v_mov_b32_e32 v18, v3
	v_mov_b32_e32 v22, v7
	v_mov_b32_e32 v24, v5
	v_mov_b32_e32 v26, v11
	v_mov_b32_e32 v34, v9
	v_mov_b32_e32 v36, v15
	v_mov_b32_e32 v38, v13
	s_cbranch_scc0 .LBB0_285
	v_lshl_add_u32 v16, s48, 2, v40
	v_ashrrev_i32_e32 v17, 31, v16
	v_lshlrev_b64 v[16:17], 13, v[16:17]
	v_lshl_add_u64 v[16:17], v[28:29], 0, v[16:17]
	global_store_dwordx4 v[16:17], v[12:15], off
	global_store_dwordx4 v[16:17], v[8:11], off offset:16
	global_store_dwordx4 v[16:17], v[4:7], off offset:32
	global_store_dwordx4 v[16:17], v[0:3], off offset:48
	s_and_saveexec_b64 s[2:3], s[36:37]
	s_cbranch_execz .LBB0_288
	ds_write_b128 v41, v[12:15]
	ds_write_b128 v41, v[8:11] offset:16
	ds_write_b128 v41, v[4:7] offset:32
	ds_write_b128 v41, v[0:3] offset:48
